# in-proj K-loop: first trip peeled with zero accumulator input, the 128 zeroing moves per unit removed
# baseline (speedup 1.0000x reference)
.LBB0_468:
	s_ashr_i32 s19, s18, 31
	s_lshl_b64 s[36:37], s[18:19], 20
	s_add_u32 s36, s54, s36
	s_addc_u32 s37, s55, s37
	s_and_b64 s[70:71], s[38:39], exec
	s_cselect_b32 s19, s37, s77
	s_cselect_b32 s69, s36, s76
	s_ashr_i32 s93, s92, 31
	s_lshl_b64 s[70:71], s[92:93], 20
	s_add_u32 s78, s52, s70
	s_addc_u32 s79, s53, s71
	s_and_b64 s[70:71], s[38:39], exec
	s_cselect_b32 s70, s79, s83
	s_cselect_b32 s71, s78, s82
	s_add_u32 s72, s82, 0x100
	s_addc_u32 s73, s83, 0
	s_add_u32 s82, s76, 0x80080
	s_mov_b64 s[62:63], s[98:99]
	s_addc_u32 s83, s77, 0
	s_mov_b32 s74, -2
	s_add_u32 s76, s82, 0xfff80080
	s_addc_u32 s77, s83, -1
	s_add_i32 s93, 0, 0x10000
	s_cmp_eq_u32 s74, 28
	s_cselect_b32 vcc_hi, s19, s77
	s_cselect_b32 vcc_lo, s69, s76
	v_add_u32_e32 v140, s93, v143
	v_add_u32_e32 v242, s93, v240
	s_cselect_b32 s77, s70, s73
	s_cselect_b32 s76, s71, s72
	s_add_i32 s75, 0, 0x14000
	ds_read_b128 v[146:149], v140
	ds_read_b128 v[150:153], v242
	ds_read_b128 v[154:157], v140 offset:2048
	ds_read_b128 v[158:161], v242 offset:2048
	v_add_u32_e32 v140, s75, v143
	v_add_u32_e32 v243, s75, v240
	ds_read_b128 v[162:165], v140
	ds_read_b128 v[166:169], v243
	ds_read_b128 v[170:173], v140 offset:2048
	ds_read_b128 v[174:177], v243 offset:2048
	v_lshl_add_u64 v[140:141], s[82:83], 0, v[138:139]
	s_add_i32 m0, s81, 0xc000
	ds_read_b128 v[178:181], v145
	ds_read_b128 v[182:185], v241
	ds_read_b128 v[190:193], v145 offset:2048
	ds_read_b128 v[194:197], v241 offset:2048
	ds_read_b128 v[198:201], v145 offset:4096
	ds_read_b128 v[216:219], v241 offset:4096
	ds_read_b128 v[220:223], v145 offset:6144
	ds_read_b128 v[224:227], v241 offset:6144
	global_load_lds_dwordx4 v[140:141], off
	v_lshl_add_u64 v[140:141], s[82:83], 0, v[136:137]
	s_add_i32 m0, s81, 0xe000
	s_nop 0
	global_load_lds_dwordx4 v[140:141], off
	s_waitcnt vmcnt(8)
	s_waitcnt lgkmcnt(0)
	s_barrier
	s_setprio 1
	s_waitcnt lgkmcnt(0)
	v_mfma_f32_16x16x32_bf16 v[126:129], v[146:149], v[178:181], 0
	v_mfma_f32_16x16x32_bf16 v[122:125], v[154:157], v[178:181], 0
	v_mfma_f32_16x16x32_bf16 v[114:117], v[146:149], v[190:193], 0
	v_mfma_f32_16x16x32_bf16 v[106:109], v[154:157], v[190:193], 0
	v_mfma_f32_16x16x32_bf16 v[98:101], v[146:149], v[198:201], 0
	v_mfma_f32_16x16x32_bf16 v[90:93], v[154:157], v[198:201], 0
	v_mfma_f32_16x16x32_bf16 v[82:85], v[146:149], v[220:223], 0
	v_mfma_f32_16x16x32_bf16 v[74:77], v[154:157], v[220:223], 0
	v_mfma_f32_16x16x32_bf16 v[126:129], v[150:153], v[182:185], v[126:129]
	v_mfma_f32_16x16x32_bf16 v[122:125], v[158:161], v[182:185], v[122:125]
	v_mfma_f32_16x16x32_bf16 v[114:117], v[150:153], v[194:197], v[114:117]
	v_mfma_f32_16x16x32_bf16 v[106:109], v[158:161], v[194:197], v[106:109]
	v_mfma_f32_16x16x32_bf16 v[98:101], v[150:153], v[216:219], v[98:101]
	v_mfma_f32_16x16x32_bf16 v[90:93], v[158:161], v[216:219], v[90:93]
	v_mfma_f32_16x16x32_bf16 v[82:85], v[150:153], v[224:227], v[82:85]
	v_mfma_f32_16x16x32_bf16 v[74:77], v[158:161], v[224:227], v[74:77]
	s_setprio 0
	s_setprio 1
	v_mfma_f32_16x16x32_bf16 v[118:121], v[162:165], v[178:181], 0
	v_mfma_f32_16x16x32_bf16 v[110:113], v[170:173], v[178:181], 0
	v_mfma_f32_16x16x32_bf16 v[102:105], v[162:165], v[190:193], 0
	v_mfma_f32_16x16x32_bf16 v[94:97], v[170:173], v[190:193], 0
	v_mfma_f32_16x16x32_bf16 v[86:89], v[162:165], v[198:201], 0
	v_mfma_f32_16x16x32_bf16 v[78:81], v[170:173], v[198:201], 0
	v_mfma_f32_16x16x32_bf16 v[70:73], v[162:165], v[220:223], 0
	v_mfma_f32_16x16x32_bf16 v[66:69], v[170:173], v[220:223], 0
	v_mfma_f32_16x16x32_bf16 v[118:121], v[166:169], v[182:185], v[118:121]
	v_mfma_f32_16x16x32_bf16 v[110:113], v[174:177], v[182:185], v[110:113]
	v_mfma_f32_16x16x32_bf16 v[102:105], v[166:169], v[194:197], v[102:105]
	v_mfma_f32_16x16x32_bf16 v[94:97], v[174:177], v[194:197], v[94:97]
	v_mfma_f32_16x16x32_bf16 v[86:89], v[166:169], v[216:219], v[86:89]
	v_mfma_f32_16x16x32_bf16 v[78:81], v[174:177], v[216:219], v[78:81]
	v_mfma_f32_16x16x32_bf16 v[70:73], v[166:169], v[224:227], v[70:73]
	v_mfma_f32_16x16x32_bf16 v[66:69], v[174:177], v[224:227], v[66:69]
	s_setprio 0
	s_barrier
	s_add_i32 s93, s93, s23
	v_lshl_add_u64 v[140:141], s[76:77], 0, v[0:1]
	s_mov_b32 m0, s93
	ds_read_b128 v[178:181], v145 offset:16384
	ds_read_b128 v[182:185], v241 offset:16384
	ds_read_b128 v[190:193], v145 offset:18432
	ds_read_b128 v[194:197], v241 offset:18432
	ds_read_b128 v[198:201], v145 offset:20480
	ds_read_b128 v[216:219], v241 offset:20480
	ds_read_b128 v[220:223], v145 offset:22528
	ds_read_b128 v[224:227], v241 offset:22528
	global_load_lds_dwordx4 v[140:141], off
	s_add_i32 m0, s93, 0x2000
	s_add_u32 s98, s76, 0x80000
	v_lshl_add_u64 v[202:203], s[76:77], 0, v[134:135]
	s_addc_u32 s99, s77, 0
	s_add_i32 s75, s75, s23
	global_load_lds_dwordx4 v[202:203], off
	v_lshl_add_u64 v[228:229], s[98:99], 0, v[0:1]
	s_mov_b32 m0, s75
	v_lshl_add_u64 v[230:231], vcc, 0, v[132:133]
	global_load_lds_dwordx4 v[228:229], off
	v_lshl_add_u64 v[228:229], s[98:99], 0, v[134:135]
	s_add_i32 m0, s75, 0x2000
	s_nop 0
	global_load_lds_dwordx4 v[228:229], off
	v_lshl_add_u64 v[228:229], vcc, 0, v[130:131]
	s_mov_b32 m0, s81
	s_nop 0
	global_load_lds_dwordx4 v[228:229], off
	s_mov_b32 m0, s60
	s_nop 0
	global_load_lds_dwordx4 v[230:231], off
	s_waitcnt vmcnt(8)
	s_waitcnt lgkmcnt(0)
	s_barrier
	s_setprio 1
	s_waitcnt lgkmcnt(0)
	v_mfma_f32_16x16x32_bf16 v[62:65], v[146:149], v[178:181], 0
	v_mfma_f32_16x16x32_bf16 v[58:61], v[154:157], v[178:181], 0
	v_mfma_f32_16x16x32_bf16 v[46:49], v[146:149], v[190:193], 0
	v_mfma_f32_16x16x32_bf16 v[42:45], v[154:157], v[190:193], 0
	v_mfma_f32_16x16x32_bf16 v[30:33], v[146:149], v[198:201], 0
	v_mfma_f32_16x16x32_bf16 v[26:29], v[154:157], v[198:201], 0
	v_mfma_f32_16x16x32_bf16 v[14:17], v[146:149], v[220:223], 0
	v_mfma_f32_16x16x32_bf16 v[10:13], v[154:157], v[220:223], 0
	v_mfma_f32_16x16x32_bf16 v[62:65], v[150:153], v[182:185], v[62:65]
	v_mfma_f32_16x16x32_bf16 v[58:61], v[158:161], v[182:185], v[58:61]
	v_mfma_f32_16x16x32_bf16 v[46:49], v[150:153], v[194:197], v[46:49]
	v_mfma_f32_16x16x32_bf16 v[42:45], v[158:161], v[194:197], v[42:45]
	v_mfma_f32_16x16x32_bf16 v[30:33], v[150:153], v[216:219], v[30:33]
	v_mfma_f32_16x16x32_bf16 v[26:29], v[158:161], v[216:219], v[26:29]
	v_mfma_f32_16x16x32_bf16 v[14:17], v[150:153], v[224:227], v[14:17]
	v_mfma_f32_16x16x32_bf16 v[10:13], v[158:161], v[224:227], v[10:13]
	s_setprio 0
	s_setprio 1
	v_mfma_f32_16x16x32_bf16 v[54:57], v[162:165], v[178:181], 0
	v_mfma_f32_16x16x32_bf16 v[50:53], v[170:173], v[178:181], 0
	v_mfma_f32_16x16x32_bf16 v[38:41], v[162:165], v[190:193], 0
	v_mfma_f32_16x16x32_bf16 v[34:37], v[170:173], v[190:193], 0
	v_mfma_f32_16x16x32_bf16 v[22:25], v[162:165], v[198:201], 0
	v_mfma_f32_16x16x32_bf16 v[18:21], v[170:173], v[198:201], 0
	v_mfma_f32_16x16x32_bf16 v[6:9], v[162:165], v[220:223], 0
	v_mfma_f32_16x16x32_bf16 v[2:5], v[170:173], v[220:223], 0
	v_mfma_f32_16x16x32_bf16 v[54:57], v[166:169], v[182:185], v[54:57]
	v_mfma_f32_16x16x32_bf16 v[50:53], v[174:177], v[182:185], v[50:53]
	v_mfma_f32_16x16x32_bf16 v[38:41], v[166:169], v[194:197], v[38:41]
	v_mfma_f32_16x16x32_bf16 v[34:37], v[174:177], v[194:197], v[34:37]
	v_mfma_f32_16x16x32_bf16 v[22:25], v[166:169], v[216:219], v[22:25]
	v_mfma_f32_16x16x32_bf16 v[18:21], v[174:177], v[216:219], v[18:21]
	v_mfma_f32_16x16x32_bf16 v[6:9], v[166:169], v[224:227], v[6:9]
	v_mfma_f32_16x16x32_bf16 v[2:5], v[174:177], v[224:227], v[2:5]
	s_setprio 0
	s_barrier
	s_add_i32 s75, 0, 0x18000
	s_add_i32 s93, 0, 0x1c000
	v_add_u32_e32 v158, s75, v143
	v_add_u32_e32 v242, s75, v240
	v_add_u32_e32 v174, s93, v143
	v_add_u32_e32 v243, s93, v240
	ds_read_b128 v[146:149], v158
	ds_read_b128 v[150:153], v242
	ds_read_b128 v[154:157], v158 offset:2048
	ds_read_b128 v[158:161], v242 offset:2048
	ds_read_b128 v[162:165], v174
	ds_read_b128 v[166:169], v243
	ds_read_b128 v[170:173], v174 offset:2048
	ds_read_b128 v[174:177], v243 offset:2048
	s_add_u32 s98, vcc_lo, 0x80000
	s_addc_u32 s99, vcc_hi, 0
	s_mov_b32 m0, s61
	v_lshl_add_u64 v[232:233], s[98:99], 0, v[130:131]
	ds_read_b128 v[178:181], v145 offset:32768
	ds_read_b128 v[182:185], v241 offset:32768
	ds_read_b128 v[190:193], v145 offset:34816
	ds_read_b128 v[194:197], v241 offset:34816
	ds_read_b128 v[198:201], v145 offset:36864
	ds_read_b128 v[216:219], v241 offset:36864
	ds_read_b128 v[220:223], v145 offset:38912
	ds_read_b128 v[224:227], v241 offset:38912
	global_load_lds_dwordx4 v[232:233], off
	v_lshl_add_u64 v[232:233], s[98:99], 0, v[132:133]
	s_mov_b32 m0, s64
	s_nop 0
	global_load_lds_dwordx4 v[232:233], off
	s_waitcnt vmcnt(8)
	s_waitcnt lgkmcnt(0)
	s_barrier
	s_setprio 1
	s_waitcnt lgkmcnt(0)
	v_mfma_f32_16x16x32_bf16 v[126:129], v[146:149], v[178:181], v[126:129]
	v_mfma_f32_16x16x32_bf16 v[122:125], v[154:157], v[178:181], v[122:125]
	v_mfma_f32_16x16x32_bf16 v[114:117], v[146:149], v[190:193], v[114:117]
	v_mfma_f32_16x16x32_bf16 v[106:109], v[154:157], v[190:193], v[106:109]
	v_mfma_f32_16x16x32_bf16 v[98:101], v[146:149], v[198:201], v[98:101]
	v_mfma_f32_16x16x32_bf16 v[90:93], v[154:157], v[198:201], v[90:93]
	v_mfma_f32_16x16x32_bf16 v[82:85], v[146:149], v[220:223], v[82:85]
	v_mfma_f32_16x16x32_bf16 v[74:77], v[154:157], v[220:223], v[74:77]
	v_mfma_f32_16x16x32_bf16 v[126:129], v[150:153], v[182:185], v[126:129]
	v_mfma_f32_16x16x32_bf16 v[122:125], v[158:161], v[182:185], v[122:125]
	v_mfma_f32_16x16x32_bf16 v[114:117], v[150:153], v[194:197], v[114:117]
	v_mfma_f32_16x16x32_bf16 v[106:109], v[158:161], v[194:197], v[106:109]
	v_mfma_f32_16x16x32_bf16 v[98:101], v[150:153], v[216:219], v[98:101]
	v_mfma_f32_16x16x32_bf16 v[90:93], v[158:161], v[216:219], v[90:93]
	v_mfma_f32_16x16x32_bf16 v[82:85], v[150:153], v[224:227], v[82:85]
	v_mfma_f32_16x16x32_bf16 v[74:77], v[158:161], v[224:227], v[74:77]
	s_setprio 0
	s_setprio 1
	v_mfma_f32_16x16x32_bf16 v[118:121], v[162:165], v[178:181], v[118:121]
	v_mfma_f32_16x16x32_bf16 v[110:113], v[170:173], v[178:181], v[110:113]
	v_mfma_f32_16x16x32_bf16 v[102:105], v[162:165], v[190:193], v[102:105]
	v_mfma_f32_16x16x32_bf16 v[94:97], v[170:173], v[190:193], v[94:97]
	v_mfma_f32_16x16x32_bf16 v[86:89], v[162:165], v[198:201], v[86:89]
	v_mfma_f32_16x16x32_bf16 v[78:81], v[170:173], v[198:201], v[78:81]
	v_mfma_f32_16x16x32_bf16 v[70:73], v[162:165], v[220:223], v[70:73]
	v_mfma_f32_16x16x32_bf16 v[66:69], v[170:173], v[220:223], v[66:69]
	v_mfma_f32_16x16x32_bf16 v[118:121], v[166:169], v[182:185], v[118:121]
	v_mfma_f32_16x16x32_bf16 v[110:113], v[174:177], v[182:185], v[110:113]
	v_mfma_f32_16x16x32_bf16 v[102:105], v[166:169], v[194:197], v[102:105]
	v_mfma_f32_16x16x32_bf16 v[94:97], v[174:177], v[194:197], v[94:97]
	v_mfma_f32_16x16x32_bf16 v[86:89], v[166:169], v[216:219], v[86:89]
	v_mfma_f32_16x16x32_bf16 v[78:81], v[174:177], v[216:219], v[78:81]
	v_mfma_f32_16x16x32_bf16 v[70:73], v[166:169], v[224:227], v[70:73]
	v_mfma_f32_16x16x32_bf16 v[66:69], v[174:177], v[224:227], v[66:69]
	s_setprio 0
	s_barrier
	s_add_i32 s75, s75, s23
	v_lshl_add_u64 v[140:141], v[140:141], 0, s[20:21]
	s_mov_b32 m0, s75
	ds_read_b128 v[178:181], v145 offset:49152
	ds_read_b128 v[182:185], v241 offset:49152
	ds_read_b128 v[190:193], v145 offset:51200
	ds_read_b128 v[194:197], v241 offset:51200
	ds_read_b128 v[198:201], v145 offset:53248
	ds_read_b128 v[216:219], v241 offset:53248
	ds_read_b128 v[220:223], v145 offset:55296
	ds_read_b128 v[224:227], v241 offset:55296
	global_load_lds_dwordx4 v[140:141], off
	s_add_i32 m0, s75, 0x2000
	s_add_u32 s76, s76, 0x80080
	v_lshl_add_u64 v[140:141], v[202:203], 0, s[20:21]
	s_addc_u32 s77, s77, 0
	s_add_i32 s75, s93, s23
	global_load_lds_dwordx4 v[140:141], off
	v_lshl_add_u64 v[140:141], s[76:77], 0, v[0:1]
	s_mov_b32 m0, s75
	s_nop 0
	global_load_lds_dwordx4 v[140:141], off
	v_lshl_add_u64 v[140:141], s[76:77], 0, v[134:135]
	s_add_i32 m0, s75, 0x2000
	s_nop 0
	global_load_lds_dwordx4 v[140:141], off
	v_lshl_add_u64 v[140:141], v[228:229], 0, s[20:21]
	s_mov_b32 m0, s65
	s_nop 0
	global_load_lds_dwordx4 v[140:141], off
	v_lshl_add_u64 v[140:141], v[230:231], 0, s[20:21]
	s_mov_b32 m0, s66
	s_nop 0
	global_load_lds_dwordx4 v[140:141], off
	s_waitcnt vmcnt(8)
	s_waitcnt lgkmcnt(0)
	s_barrier
	s_setprio 1
	s_waitcnt lgkmcnt(0)
	v_mfma_f32_16x16x32_bf16 v[62:65], v[146:149], v[178:181], v[62:65]
	v_mfma_f32_16x16x32_bf16 v[58:61], v[154:157], v[178:181], v[58:61]
	v_mfma_f32_16x16x32_bf16 v[46:49], v[146:149], v[190:193], v[46:49]
	v_mfma_f32_16x16x32_bf16 v[42:45], v[154:157], v[190:193], v[42:45]
	v_mfma_f32_16x16x32_bf16 v[30:33], v[146:149], v[198:201], v[30:33]
	v_mfma_f32_16x16x32_bf16 v[26:29], v[154:157], v[198:201], v[26:29]
	v_mfma_f32_16x16x32_bf16 v[14:17], v[146:149], v[220:223], v[14:17]
	v_mfma_f32_16x16x32_bf16 v[10:13], v[154:157], v[220:223], v[10:13]
	v_mfma_f32_16x16x32_bf16 v[62:65], v[150:153], v[182:185], v[62:65]
	v_mfma_f32_16x16x32_bf16 v[58:61], v[158:161], v[182:185], v[58:61]
	v_mfma_f32_16x16x32_bf16 v[46:49], v[150:153], v[194:197], v[46:49]
	v_mfma_f32_16x16x32_bf16 v[42:45], v[158:161], v[194:197], v[42:45]
	v_mfma_f32_16x16x32_bf16 v[30:33], v[150:153], v[216:219], v[30:33]
	v_mfma_f32_16x16x32_bf16 v[26:29], v[158:161], v[216:219], v[26:29]
	v_mfma_f32_16x16x32_bf16 v[14:17], v[150:153], v[224:227], v[14:17]
	v_mfma_f32_16x16x32_bf16 v[10:13], v[158:161], v[224:227], v[10:13]
	s_setprio 0
	s_setprio 1
	v_mfma_f32_16x16x32_bf16 v[54:57], v[162:165], v[178:181], v[54:57]
	v_mfma_f32_16x16x32_bf16 v[50:53], v[170:173], v[178:181], v[50:53]
	v_mfma_f32_16x16x32_bf16 v[38:41], v[162:165], v[190:193], v[38:41]
	v_mfma_f32_16x16x32_bf16 v[34:37], v[170:173], v[190:193], v[34:37]
	v_mfma_f32_16x16x32_bf16 v[22:25], v[162:165], v[198:201], v[22:25]
	v_mfma_f32_16x16x32_bf16 v[18:21], v[170:173], v[198:201], v[18:21]
	v_mfma_f32_16x16x32_bf16 v[6:9], v[162:165], v[220:223], v[6:9]
	v_mfma_f32_16x16x32_bf16 v[2:5], v[170:173], v[220:223], v[2:5]
	v_mfma_f32_16x16x32_bf16 v[54:57], v[166:169], v[182:185], v[54:57]
	v_mfma_f32_16x16x32_bf16 v[50:53], v[174:177], v[182:185], v[50:53]
	v_mfma_f32_16x16x32_bf16 v[38:41], v[166:169], v[194:197], v[38:41]
	v_mfma_f32_16x16x32_bf16 v[34:37], v[174:177], v[194:197], v[34:37]
	v_mfma_f32_16x16x32_bf16 v[22:25], v[166:169], v[216:219], v[22:25]
	v_mfma_f32_16x16x32_bf16 v[18:21], v[174:177], v[216:219], v[18:21]
	v_mfma_f32_16x16x32_bf16 v[6:9], v[166:169], v[224:227], v[6:9]
	v_mfma_f32_16x16x32_bf16 v[2:5], v[174:177], v[224:227], v[2:5]
	s_setprio 0
	s_barrier
	s_add_i32 s74, s74, 2
	s_add_u32 s72, s72, 0x100
	s_addc_u32 s73, s73, 0
	s_add_u32 s82, s82, 0x100
	s_addc_u32 s83, s83, 0
